# v44: + hand-written topk score stage (all q/key fragment loads in flight, counted waits)
# speedup vs baseline: 1.1191x; 1.0009x over previous
; __device__ void topk_unit(const Params& p, unsigned char* smem, int unit) {
;     ...
;   for (int k = 0; k < 2; ++k) {
;     f32x4 sc[8];
; #pragma unroll
;     for (int i = 0; i < 8; ++i) sc[i] = (f32x4){0, 0, 0, 0};
; #pragma unroll
;     for (int ks = 0; ks < 4; ++ks) {
;       bf16x8 qf = as_frag(*(const u32x4*)(qg + (size_t)(tok0 + l15) * DM + h * 256 + k * 128 + ks * 32 + q4 * 8));
; #pragma unroll
;       for (int nt = 0; nt < 8; ++nt) {
;         bf16x8 kf = as_frag(*(const u32x4*)(kb + (size_t)((h * 2 + k) * 128 + nt * 16 + l15) * 128 + ks * 32 + q4 * 8));
;         sc[nt] = mfma16(kf, qf, sc[nt]);
;       }
;     }
.LBB0_1085:
	v_lshlrev_b32_e32 v26, 3, v167
	v_and_b32_e32 v26, 0xffffffc0, v26
	v_or3_b32 v26, v26, v97, v96
	v_ashrrev_i32_e32 v27, 31, v26
	v_and_b32_e32 v94, 7, v167
	v_lshlrev_b64 v[26:27], 12, v[26:27]
	v_lshl_add_u64 v[26:27], s[36:37], 0, v[26:27]
	v_lshlrev_b32_e32 v62, 9, v94
	v_lshl_add_u64 v[26:27], v[26:27], 0, v[62:63]
	v_lshl_add_u64 v[60:61], v[26:27], 0, v[86:87]
	v_lshl_or_b32 v62, v94, 16, v117
	v_lshl_add_u64 v[92:93], v[66:67], 0, v[62:63]
	s_mov_b64 s[8:9], 0x1000
	s_mov_b64 s[10:11], 0x8000
	v_sub_u32_e32 v165, 15, v98
	v_sub_u32_e32 v166, 14, v98
	v_sub_u32_e32 v79, 13, v98
	v_sub_u32_e32 v89, 12, v98
	global_load_dwordx4 v[28:31], v[60:61], off
	global_load_dwordx4 v[32:35], v[60:61], off offset:64
	global_load_dwordx4 v[36:39], v[60:61], off offset:128
	global_load_dwordx4 v[40:43], v[60:61], off offset:192
	v_lshl_add_u64 v[94:95], v[92:93], 0, 0
	global_load_dwordx4 v[168:171], v[94:95], off
	global_load_dwordx4 v[172:175], v[94:95], off offset:64
	global_load_dwordx4 v[176:179], v[94:95], off offset:128
	global_load_dwordx4 v[180:183], v[94:95], off offset:192
	v_lshl_add_u64 v[94:95], v[94:95], 0, s[8:9]
	global_load_dwordx4 v[184:187], v[94:95], off
	global_load_dwordx4 v[188:191], v[94:95], off offset:64
	global_load_dwordx4 v[192:195], v[94:95], off offset:128
	global_load_dwordx4 v[196:199], v[94:95], off offset:192
	v_lshl_add_u64 v[94:95], v[94:95], 0, s[8:9]
	global_load_dwordx4 v[200:203], v[94:95], off
	global_load_dwordx4 v[204:207], v[94:95], off offset:64
	global_load_dwordx4 v[208:211], v[94:95], off offset:128
	global_load_dwordx4 v[212:215], v[94:95], off offset:192
	v_lshl_add_u64 v[94:95], v[94:95], 0, s[8:9]
	global_load_dwordx4 v[216:219], v[94:95], off
	global_load_dwordx4 v[220:223], v[94:95], off offset:64
	global_load_dwordx4 v[224:227], v[94:95], off offset:128
	global_load_dwordx4 v[228:231], v[94:95], off offset:192
	v_lshl_add_u64 v[94:95], v[94:95], 0, s[8:9]
	global_load_dwordx4 v[232:235], v[94:95], off
	global_load_dwordx4 v[236:239], v[94:95], off offset:64
	global_load_dwordx4 v[240:243], v[94:95], off offset:128
	global_load_dwordx4 v[244:247], v[94:95], off offset:192
	v_lshl_add_u64 v[94:95], v[94:95], 0, s[8:9]
	global_load_dwordx4 v[140:143], v[94:95], off
	global_load_dwordx4 v[144:147], v[94:95], off offset:64
	global_load_dwordx4 v[148:151], v[94:95], off offset:128
	global_load_dwordx4 v[152:155], v[94:95], off offset:192
	v_lshl_add_u64 v[94:95], v[94:95], 0, s[8:9]
	global_load_dwordx4 v[156:159], v[94:95], off
	global_load_dwordx4 v[160:163], v[94:95], off offset:64
	global_load_dwordx4 v[2:5], v[94:95], off offset:128
	global_load_dwordx4 v[6:9], v[94:95], off offset:192
	v_lshl_add_u64 v[94:95], v[94:95], 0, s[8:9]
	global_load_dwordx4 v[10:13], v[94:95], off
	global_load_dwordx4 v[14:17], v[94:95], off offset:64
	global_load_dwordx4 v[18:21], v[94:95], off offset:128
	global_load_dwordx4 v[22:25], v[94:95], off offset:192
	s_waitcnt vmcnt(28)
	v_mfma_f32_16x16x32_bf16 v[122:125], v[168:171], v[28:31], 0
	v_mfma_f32_16x16x32_bf16 v[122:125], v[172:175], v[32:35], v[122:125]
	v_mfma_f32_16x16x32_bf16 v[122:125], v[176:179], v[36:39], v[122:125]
	v_mfma_f32_16x16x32_bf16 v[122:125], v[180:183], v[40:43], v[122:125]
	s_waitcnt vmcnt(24)
	v_mfma_f32_16x16x32_bf16 v[126:129], v[184:187], v[28:31], 0
	v_mfma_f32_16x16x32_bf16 v[126:129], v[188:191], v[32:35], v[126:129]
	v_mfma_f32_16x16x32_bf16 v[126:129], v[192:195], v[36:39], v[126:129]
	v_mfma_f32_16x16x32_bf16 v[126:129], v[196:199], v[40:43], v[126:129]
	s_waitcnt vmcnt(20)
	v_mfma_f32_16x16x32_bf16 v[130:133], v[200:203], v[28:31], 0
	v_mfma_f32_16x16x32_bf16 v[130:133], v[204:207], v[32:35], v[130:133]
	v_mfma_f32_16x16x32_bf16 v[130:133], v[208:211], v[36:39], v[130:133]
	v_mfma_f32_16x16x32_bf16 v[130:133], v[212:215], v[40:43], v[130:133]
	s_waitcnt vmcnt(16)
	v_mfma_f32_16x16x32_bf16 v[134:137], v[216:219], v[28:31], 0
	v_mfma_f32_16x16x32_bf16 v[134:137], v[220:223], v[32:35], v[134:137]
	v_mfma_f32_16x16x32_bf16 v[134:137], v[224:227], v[36:39], v[134:137]
	v_mfma_f32_16x16x32_bf16 v[134:137], v[228:231], v[40:43], v[134:137]
	s_waitcnt vmcnt(12)
	v_mfma_f32_16x16x32_bf16 v[44:47], v[232:235], v[28:31], 0
	v_mfma_f32_16x16x32_bf16 v[44:47], v[236:239], v[32:35], v[44:47]
	v_mfma_f32_16x16x32_bf16 v[44:47], v[240:243], v[36:39], v[44:47]
	v_mfma_f32_16x16x32_bf16 v[44:47], v[244:247], v[40:43], v[44:47]
	s_waitcnt vmcnt(8)
	v_mfma_f32_16x16x32_bf16 v[48:51], v[140:143], v[28:31], 0
	v_mfma_f32_16x16x32_bf16 v[48:51], v[144:147], v[32:35], v[48:51]
	v_mfma_f32_16x16x32_bf16 v[48:51], v[148:151], v[36:39], v[48:51]
	v_mfma_f32_16x16x32_bf16 v[48:51], v[152:155], v[40:43], v[48:51]
	s_waitcnt vmcnt(4)
	v_mfma_f32_16x16x32_bf16 v[52:55], v[156:159], v[28:31], 0
	v_mfma_f32_16x16x32_bf16 v[52:55], v[160:163], v[32:35], v[52:55]
	v_mfma_f32_16x16x32_bf16 v[52:55], v[2:5], v[36:39], v[52:55]
	v_mfma_f32_16x16x32_bf16 v[52:55], v[6:9], v[40:43], v[52:55]
	s_waitcnt vmcnt(0)
; __device__ void topk_unit(const Params& p, unsigned char* smem, int unit) {
;     ...
;       bf16x8 qf = as_frag(*(const u32x4*)(qg + (size_t)(tok0 + l15) * DM + h * 256 + k * 128 + ks * 32 + q4 * 8));
; #pragma unroll
;       for (int nt = 0; nt < 8; ++nt) {
;         bf16x8 kf = as_frag(*(const u32x4*)(kb + (size_t)((h * 2 + k) * 128 + nt * 16 + l15) * 128 + ks * 32 + q4 * 8));
;         sc[nt] = mfma16(kf, qf, sc[nt]);
;       }
;     }
; #pragma unroll
;     for (int nt = 0; nt < 8; ++nt) {
;       const int n = nt * 16 + q4 * 4;
;       u32x4 kk;
; #pragma unroll
;       for (int r = 0; r < 4; ++r) kk[r] = (ord_key(sc[nt][r]) & ~127u) | (unsigned)(127 - (n + r));
;       *(u32x4*)(S + l15 * 260 + k * 128 + n) = kk;
	v_mfma_f32_16x16x32_bf16 v[56:59], v[10:13], v[28:31], 0
	v_mfma_f32_16x16x32_bf16 v[56:59], v[14:17], v[32:35], v[56:59]
	v_mfma_f32_16x16x32_bf16 v[56:59], v[18:21], v[36:39], v[56:59]
	v_mfma_f32_16x16x32_bf16 v[56:59], v[22:25], v[40:43], v[56:59]
	global_load_dwordx4 v[28:31], v[60:61], off offset:256
	global_load_dwordx4 v[32:35], v[60:61], off offset:320
	global_load_dwordx4 v[36:39], v[60:61], off offset:384
	global_load_dwordx4 v[40:43], v[60:61], off offset:448
	v_lshl_add_u64 v[94:95], v[92:93], 0, s[10:11]
	global_load_dwordx4 v[168:171], v[94:95], off
	global_load_dwordx4 v[172:175], v[94:95], off offset:64
	global_load_dwordx4 v[176:179], v[94:95], off offset:128
	global_load_dwordx4 v[180:183], v[94:95], off offset:192
	v_lshl_add_u64 v[94:95], v[94:95], 0, s[8:9]
	global_load_dwordx4 v[184:187], v[94:95], off
	global_load_dwordx4 v[188:191], v[94:95], off offset:64
	global_load_dwordx4 v[192:195], v[94:95], off offset:128
	global_load_dwordx4 v[196:199], v[94:95], off offset:192
	v_lshl_add_u64 v[94:95], v[94:95], 0, s[8:9]
	global_load_dwordx4 v[200:203], v[94:95], off
	global_load_dwordx4 v[204:207], v[94:95], off offset:64
	global_load_dwordx4 v[208:211], v[94:95], off offset:128
	global_load_dwordx4 v[212:215], v[94:95], off offset:192
	v_lshl_add_u64 v[94:95], v[94:95], 0, s[8:9]
	global_load_dwordx4 v[216:219], v[94:95], off
	global_load_dwordx4 v[220:223], v[94:95], off offset:64
	global_load_dwordx4 v[224:227], v[94:95], off offset:128
	global_load_dwordx4 v[228:231], v[94:95], off offset:192
	v_lshl_add_u64 v[94:95], v[94:95], 0, s[8:9]
	global_load_dwordx4 v[232:235], v[94:95], off
	global_load_dwordx4 v[236:239], v[94:95], off offset:64
	global_load_dwordx4 v[240:243], v[94:95], off offset:128
	global_load_dwordx4 v[244:247], v[94:95], off offset:192
	v_lshl_add_u64 v[94:95], v[94:95], 0, s[8:9]
	global_load_dwordx4 v[140:143], v[94:95], off
	global_load_dwordx4 v[144:147], v[94:95], off offset:64
	global_load_dwordx4 v[148:151], v[94:95], off offset:128
	global_load_dwordx4 v[152:155], v[94:95], off offset:192
	v_lshl_add_u64 v[94:95], v[94:95], 0, s[8:9]
	global_load_dwordx4 v[156:159], v[94:95], off
	global_load_dwordx4 v[160:163], v[94:95], off offset:64
	global_load_dwordx4 v[2:5], v[94:95], off offset:128
	global_load_dwordx4 v[6:9], v[94:95], off offset:192
	v_lshl_add_u64 v[94:95], v[94:95], 0, s[8:9]
	global_load_dwordx4 v[10:13], v[94:95], off
	global_load_dwordx4 v[14:17], v[94:95], off offset:64
	global_load_dwordx4 v[18:21], v[94:95], off offset:128
	global_load_dwordx4 v[22:25], v[94:95], off offset:192
	v_ashrrev_i32_e32 v26, 31, v122
	v_or_b32_e32 v26, v118, v26
	v_xor_b32_e32 v122, v122, v26
	v_and_or_b32 v122, v122, s54, v165
	v_or_b32_e32 v122, 112, v122
	v_ashrrev_i32_e32 v27, 31, v123
	v_or_b32_e32 v27, v118, v27
	v_xor_b32_e32 v123, v123, v27
	v_and_or_b32 v123, v123, s54, v166
	v_or_b32_e32 v123, 112, v123
	v_ashrrev_i32_e32 v26, 31, v124
	v_or_b32_e32 v26, v118, v26
	v_xor_b32_e32 v124, v124, v26
	v_and_or_b32 v124, v124, s54, v79
	v_or_b32_e32 v124, 112, v124
	v_ashrrev_i32_e32 v27, 31, v125
	v_or_b32_e32 v27, v118, v27
	v_xor_b32_e32 v125, v125, v27
	v_and_or_b32 v125, v125, s54, v89
	v_or_b32_e32 v125, 112, v125
	ds_write_b128 v100, v[122:125]
	v_ashrrev_i32_e32 v26, 31, v126
	v_or_b32_e32 v26, v118, v26
	v_xor_b32_e32 v126, v126, v26
	v_and_or_b32 v126, v126, s54, v165
	v_or_b32_e32 v126, 96, v126
	v_ashrrev_i32_e32 v27, 31, v127
	v_or_b32_e32 v27, v118, v27
	v_xor_b32_e32 v127, v127, v27
	v_and_or_b32 v127, v127, s54, v166
	v_or_b32_e32 v127, 96, v127
	v_ashrrev_i32_e32 v26, 31, v128
	v_or_b32_e32 v26, v118, v26
	v_xor_b32_e32 v128, v128, v26
	v_and_or_b32 v128, v128, s54, v79
	v_or_b32_e32 v128, 96, v128
	v_ashrrev_i32_e32 v27, 31, v129
	v_or_b32_e32 v27, v118, v27
	v_xor_b32_e32 v129, v129, v27
	v_and_or_b32 v129, v129, s54, v89
	v_or_b32_e32 v129, 96, v129
	ds_write_b128 v100, v[126:129] offset:64
	v_ashrrev_i32_e32 v26, 31, v130
	v_or_b32_e32 v26, v118, v26
	v_xor_b32_e32 v130, v130, v26
	v_and_or_b32 v130, v130, s54, v165
	v_or_b32_e32 v130, 80, v130
	v_ashrrev_i32_e32 v27, 31, v131
	v_or_b32_e32 v27, v118, v27
	v_xor_b32_e32 v131, v131, v27
	v_and_or_b32 v131, v131, s54, v166
	v_or_b32_e32 v131, 80, v131
	v_ashrrev_i32_e32 v26, 31, v132
	v_or_b32_e32 v26, v118, v26
	v_xor_b32_e32 v132, v132, v26
	v_and_or_b32 v132, v132, s54, v79
	v_or_b32_e32 v132, 80, v132
	v_ashrrev_i32_e32 v27, 31, v133
	v_or_b32_e32 v27, v118, v27
	v_xor_b32_e32 v133, v133, v27
	v_and_or_b32 v133, v133, s54, v89
	v_or_b32_e32 v133, 80, v133
	ds_write_b128 v100, v[130:133] offset:128
	v_ashrrev_i32_e32 v26, 31, v134
	v_or_b32_e32 v26, v118, v26
	v_xor_b32_e32 v134, v134, v26
	v_and_or_b32 v134, v134, s54, v165
	v_or_b32_e32 v134, 64, v134
	v_ashrrev_i32_e32 v27, 31, v135
	v_or_b32_e32 v27, v118, v27
	v_xor_b32_e32 v135, v135, v27
	v_and_or_b32 v135, v135, s54, v166
	v_or_b32_e32 v135, 64, v135
	v_ashrrev_i32_e32 v26, 31, v136
	v_or_b32_e32 v26, v118, v26
	v_xor_b32_e32 v136, v136, v26
	v_and_or_b32 v136, v136, s54, v79
	v_or_b32_e32 v136, 64, v136
	v_ashrrev_i32_e32 v27, 31, v137
	v_or_b32_e32 v27, v118, v27
	v_xor_b32_e32 v137, v137, v27
	v_and_or_b32 v137, v137, s54, v89
	v_or_b32_e32 v137, 64, v137
	ds_write_b128 v100, v[134:137] offset:192
	v_ashrrev_i32_e32 v26, 31, v44
	v_or_b32_e32 v26, v118, v26
	v_xor_b32_e32 v44, v44, v26
	v_and_or_b32 v44, v44, s54, v165
	v_or_b32_e32 v44, 48, v44
	v_ashrrev_i32_e32 v27, 31, v45
	v_or_b32_e32 v27, v118, v27
	v_xor_b32_e32 v45, v45, v27
	v_and_or_b32 v45, v45, s54, v166
	v_or_b32_e32 v45, 48, v45
	v_ashrrev_i32_e32 v26, 31, v46
	v_or_b32_e32 v26, v118, v26
; __device__ void topk_unit(const Params& p, unsigned char* smem, int unit) {
;     ...
;     }
; #pragma unroll
;     for (int nt = 0; nt < 8; ++nt) {
;       const int n = nt * 16 + q4 * 4;
;       u32x4 kk;
; #pragma unroll
;       for (int r = 0; r < 4; ++r) kk[r] = (ord_key(sc[nt][r]) & ~127u) | (unsigned)(127 - (n + r));
;       *(u32x4*)(S + l15 * 260 + k * 128 + n) = kk;
	v_xor_b32_e32 v46, v46, v26
	v_and_or_b32 v46, v46, s54, v79
	v_or_b32_e32 v46, 48, v46
	v_ashrrev_i32_e32 v27, 31, v47
	v_or_b32_e32 v27, v118, v27
	v_xor_b32_e32 v47, v47, v27
	v_and_or_b32 v47, v47, s54, v89
	v_or_b32_e32 v47, 48, v47
	ds_write_b128 v100, v[44:47] offset:256
	v_ashrrev_i32_e32 v26, 31, v48
	v_or_b32_e32 v26, v118, v26
	v_xor_b32_e32 v48, v48, v26
	v_and_or_b32 v48, v48, s54, v165
	v_or_b32_e32 v48, 32, v48
	v_ashrrev_i32_e32 v27, 31, v49
	v_or_b32_e32 v27, v118, v27
	v_xor_b32_e32 v49, v49, v27
	v_and_or_b32 v49, v49, s54, v166
	v_or_b32_e32 v49, 32, v49
	v_ashrrev_i32_e32 v26, 31, v50
	v_or_b32_e32 v26, v118, v26
	v_xor_b32_e32 v50, v50, v26
	v_and_or_b32 v50, v50, s54, v79
	v_or_b32_e32 v50, 32, v50
	v_ashrrev_i32_e32 v27, 31, v51
	v_or_b32_e32 v27, v118, v27
	v_xor_b32_e32 v51, v51, v27
	v_and_or_b32 v51, v51, s54, v89
	v_or_b32_e32 v51, 32, v51
	ds_write_b128 v100, v[48:51] offset:320
	v_ashrrev_i32_e32 v26, 31, v52
	v_or_b32_e32 v26, v118, v26
	v_xor_b32_e32 v52, v52, v26
	v_and_or_b32 v52, v52, s54, v165
	v_or_b32_e32 v52, 16, v52
	v_ashrrev_i32_e32 v27, 31, v53
	v_or_b32_e32 v27, v118, v27
	v_xor_b32_e32 v53, v53, v27
	v_and_or_b32 v53, v53, s54, v166
	v_or_b32_e32 v53, 16, v53
	v_ashrrev_i32_e32 v26, 31, v54
	v_or_b32_e32 v26, v118, v26
	v_xor_b32_e32 v54, v54, v26
	v_and_or_b32 v54, v54, s54, v79
	v_or_b32_e32 v54, 16, v54
	v_ashrrev_i32_e32 v27, 31, v55
	v_or_b32_e32 v27, v118, v27
	v_xor_b32_e32 v55, v55, v27
	v_and_or_b32 v55, v55, s54, v89
	v_or_b32_e32 v55, 16, v55
	ds_write_b128 v100, v[52:55] offset:384
	v_ashrrev_i32_e32 v26, 31, v56
	v_or_b32_e32 v26, v118, v26
	v_xor_b32_e32 v56, v56, v26
	v_and_or_b32 v56, v56, s54, v165
	v_ashrrev_i32_e32 v27, 31, v57
	v_or_b32_e32 v27, v118, v27
	v_xor_b32_e32 v57, v57, v27
	v_and_or_b32 v57, v57, s54, v166
	v_ashrrev_i32_e32 v26, 31, v58
	v_or_b32_e32 v26, v118, v26
	v_xor_b32_e32 v58, v58, v26
	v_and_or_b32 v58, v58, s54, v79
	v_ashrrev_i32_e32 v27, 31, v59
	v_or_b32_e32 v27, v118, v27
	v_xor_b32_e32 v59, v59, v27
	v_and_or_b32 v59, v59, s54, v89
	ds_write_b128 v100, v[56:59] offset:448
	s_waitcnt vmcnt(28)
	v_mfma_f32_16x16x32_bf16 v[122:125], v[168:171], v[28:31], 0
	v_mfma_f32_16x16x32_bf16 v[122:125], v[172:175], v[32:35], v[122:125]
	v_mfma_f32_16x16x32_bf16 v[122:125], v[176:179], v[36:39], v[122:125]
	v_mfma_f32_16x16x32_bf16 v[122:125], v[180:183], v[40:43], v[122:125]
	s_waitcnt vmcnt(24)
	v_mfma_f32_16x16x32_bf16 v[126:129], v[184:187], v[28:31], 0
	v_mfma_f32_16x16x32_bf16 v[126:129], v[188:191], v[32:35], v[126:129]
	v_mfma_f32_16x16x32_bf16 v[126:129], v[192:195], v[36:39], v[126:129]
	v_mfma_f32_16x16x32_bf16 v[126:129], v[196:199], v[40:43], v[126:129]
	s_waitcnt vmcnt(20)
	v_mfma_f32_16x16x32_bf16 v[130:133], v[200:203], v[28:31], 0
	v_mfma_f32_16x16x32_bf16 v[130:133], v[204:207], v[32:35], v[130:133]
	v_mfma_f32_16x16x32_bf16 v[130:133], v[208:211], v[36:39], v[130:133]
	v_mfma_f32_16x16x32_bf16 v[130:133], v[212:215], v[40:43], v[130:133]
	s_waitcnt vmcnt(16)
	v_mfma_f32_16x16x32_bf16 v[134:137], v[216:219], v[28:31], 0
	v_mfma_f32_16x16x32_bf16 v[134:137], v[220:223], v[32:35], v[134:137]
	v_mfma_f32_16x16x32_bf16 v[134:137], v[224:227], v[36:39], v[134:137]
	v_mfma_f32_16x16x32_bf16 v[134:137], v[228:231], v[40:43], v[134:137]
	s_waitcnt vmcnt(12)
	v_mfma_f32_16x16x32_bf16 v[44:47], v[232:235], v[28:31], 0
	v_mfma_f32_16x16x32_bf16 v[44:47], v[236:239], v[32:35], v[44:47]
	v_mfma_f32_16x16x32_bf16 v[44:47], v[240:243], v[36:39], v[44:47]
	v_mfma_f32_16x16x32_bf16 v[44:47], v[244:247], v[40:43], v[44:47]
	s_waitcnt vmcnt(8)
	v_mfma_f32_16x16x32_bf16 v[48:51], v[140:143], v[28:31], 0
	v_mfma_f32_16x16x32_bf16 v[48:51], v[144:147], v[32:35], v[48:51]
	v_mfma_f32_16x16x32_bf16 v[48:51], v[148:151], v[36:39], v[48:51]
	v_mfma_f32_16x16x32_bf16 v[48:51], v[152:155], v[40:43], v[48:51]
	s_waitcnt vmcnt(4)
	v_mfma_f32_16x16x32_bf16 v[52:55], v[156:159], v[28:31], 0
	v_mfma_f32_16x16x32_bf16 v[52:55], v[160:163], v[32:35], v[52:55]
	v_mfma_f32_16x16x32_bf16 v[52:55], v[2:5], v[36:39], v[52:55]
	v_mfma_f32_16x16x32_bf16 v[52:55], v[6:9], v[40:43], v[52:55]
	s_waitcnt vmcnt(0)
; __device__ void topk_unit(const Params& p, unsigned char* smem, int unit) {
;     ...
;       bf16x8 qf = as_frag(*(const u32x4*)(qg + (size_t)(tok0 + l15) * DM + h * 256 + k * 128 + ks * 32 + q4 * 8));
; #pragma unroll
;       for (int nt = 0; nt < 8; ++nt) {
;         bf16x8 kf = as_frag(*(const u32x4*)(kb + (size_t)((h * 2 + k) * 128 + nt * 16 + l15) * 128 + ks * 32 + q4 * 8));
;         sc[nt] = mfma16(kf, qf, sc[nt]);
;       }
;     }
; #pragma unroll
;     for (int nt = 0; nt < 8; ++nt) {
;       const int n = nt * 16 + q4 * 4;
;       u32x4 kk;
; #pragma unroll
;       for (int r = 0; r < 4; ++r) kk[r] = (ord_key(sc[nt][r]) & ~127u) | (unsigned)(127 - (n + r));
;       *(u32x4*)(S + l15 * 260 + k * 128 + n) = kk;
;     }
;   }
;   const unsigned ct = cand_tab[lane];
;   const int ca = ct >> 4, cbb = ct & 15;
;   int* idxo = (int*)(ws + OFF_IDX);
;   float* go = (float*)(ws + OFF_G);
	v_mfma_f32_16x16x32_bf16 v[56:59], v[10:13], v[28:31], 0
	v_mfma_f32_16x16x32_bf16 v[56:59], v[14:17], v[32:35], v[56:59]
	v_mfma_f32_16x16x32_bf16 v[56:59], v[18:21], v[36:39], v[56:59]
	v_mfma_f32_16x16x32_bf16 v[56:59], v[22:25], v[40:43], v[56:59]
	v_and_or_b32 v26, v114, s52, v97
	v_ashrrev_i32_e32 v27, 31, v26
	v_and_b32_e32 v62, 7, v115
	v_lshlrev_b64 v[90:91], 7, v[26:27]
	s_mov_b32 s12, 0
	v_lshl_or_b32 v90, v62, 4, v90
	s_nop 4
	v_ashrrev_i32_e32 v26, 31, v122
	v_or_b32_e32 v26, v118, v26
	v_xor_b32_e32 v122, v122, v26
	v_and_or_b32 v122, v122, s54, v165
	v_or_b32_e32 v122, 112, v122
	v_ashrrev_i32_e32 v27, 31, v123
	v_or_b32_e32 v27, v118, v27
	v_xor_b32_e32 v123, v123, v27
	v_and_or_b32 v123, v123, s54, v166
	v_or_b32_e32 v123, 112, v123
	v_ashrrev_i32_e32 v26, 31, v124
	v_or_b32_e32 v26, v118, v26
	v_xor_b32_e32 v124, v124, v26
	v_and_or_b32 v124, v124, s54, v79
	v_or_b32_e32 v124, 112, v124
	v_ashrrev_i32_e32 v27, 31, v125
	v_or_b32_e32 v27, v118, v27
	v_xor_b32_e32 v125, v125, v27
	v_and_or_b32 v125, v125, s54, v89
	v_or_b32_e32 v125, 112, v125
	ds_write_b128 v100, v[122:125] offset:512
	v_ashrrev_i32_e32 v26, 31, v126
	v_or_b32_e32 v26, v118, v26
	v_xor_b32_e32 v126, v126, v26
	v_and_or_b32 v126, v126, s54, v165
	v_or_b32_e32 v126, 96, v126
	v_ashrrev_i32_e32 v27, 31, v127
	v_or_b32_e32 v27, v118, v27
	v_xor_b32_e32 v127, v127, v27
	v_and_or_b32 v127, v127, s54, v166
	v_or_b32_e32 v127, 96, v127
	v_ashrrev_i32_e32 v26, 31, v128
	v_or_b32_e32 v26, v118, v26
	v_xor_b32_e32 v128, v128, v26
	v_and_or_b32 v128, v128, s54, v79
	v_or_b32_e32 v128, 96, v128
	v_ashrrev_i32_e32 v27, 31, v129
	v_or_b32_e32 v27, v118, v27
	v_xor_b32_e32 v129, v129, v27
	v_and_or_b32 v129, v129, s54, v89
	v_or_b32_e32 v129, 96, v129
	ds_write_b128 v100, v[126:129] offset:576
	v_ashrrev_i32_e32 v26, 31, v130
	v_or_b32_e32 v26, v118, v26
	v_xor_b32_e32 v130, v130, v26
	v_and_or_b32 v130, v130, s54, v165
	v_or_b32_e32 v130, 80, v130
	v_ashrrev_i32_e32 v27, 31, v131
	v_or_b32_e32 v27, v118, v27
	v_xor_b32_e32 v131, v131, v27
	v_and_or_b32 v131, v131, s54, v166
	v_or_b32_e32 v131, 80, v131
	v_ashrrev_i32_e32 v26, 31, v132
	v_or_b32_e32 v26, v118, v26
	v_xor_b32_e32 v132, v132, v26
	v_and_or_b32 v132, v132, s54, v79
	v_or_b32_e32 v132, 80, v132
	v_ashrrev_i32_e32 v27, 31, v133
	v_or_b32_e32 v27, v118, v27
	v_xor_b32_e32 v133, v133, v27
	v_and_or_b32 v133, v133, s54, v89
	v_or_b32_e32 v133, 80, v133
	ds_write_b128 v100, v[130:133] offset:640
	v_ashrrev_i32_e32 v26, 31, v134
	v_or_b32_e32 v26, v118, v26
	v_xor_b32_e32 v134, v134, v26
	v_and_or_b32 v134, v134, s54, v165
	v_or_b32_e32 v134, 64, v134
	v_ashrrev_i32_e32 v27, 31, v135
	v_or_b32_e32 v27, v118, v27
	v_xor_b32_e32 v135, v135, v27
	v_and_or_b32 v135, v135, s54, v166
	v_or_b32_e32 v135, 64, v135
	v_ashrrev_i32_e32 v26, 31, v136
	v_or_b32_e32 v26, v118, v26
	v_xor_b32_e32 v136, v136, v26
	v_and_or_b32 v136, v136, s54, v79
	v_or_b32_e32 v136, 64, v136
	v_ashrrev_i32_e32 v27, 31, v137
	v_or_b32_e32 v27, v118, v27
	v_xor_b32_e32 v137, v137, v27
	v_and_or_b32 v137, v137, s54, v89
	v_or_b32_e32 v137, 64, v137
	ds_write_b128 v100, v[134:137] offset:704
	v_ashrrev_i32_e32 v26, 31, v44
	v_or_b32_e32 v26, v118, v26
	v_xor_b32_e32 v44, v44, v26
	v_and_or_b32 v44, v44, s54, v165
	v_or_b32_e32 v44, 48, v44
	v_ashrrev_i32_e32 v27, 31, v45
	v_or_b32_e32 v27, v118, v27
	v_xor_b32_e32 v45, v45, v27
	v_and_or_b32 v45, v45, s54, v166
	v_or_b32_e32 v45, 48, v45
	v_ashrrev_i32_e32 v26, 31, v46
	v_or_b32_e32 v26, v118, v26
	v_xor_b32_e32 v46, v46, v26
	v_and_or_b32 v46, v46, s54, v79
	v_or_b32_e32 v46, 48, v46
	v_ashrrev_i32_e32 v27, 31, v47
	v_or_b32_e32 v27, v118, v27
	v_xor_b32_e32 v47, v47, v27
	v_and_or_b32 v47, v47, s54, v89
	v_or_b32_e32 v47, 48, v47
	ds_write_b128 v100, v[44:47] offset:768
	v_ashrrev_i32_e32 v26, 31, v48
	v_or_b32_e32 v26, v118, v26
	v_xor_b32_e32 v48, v48, v26
	v_and_or_b32 v48, v48, s54, v165
	v_or_b32_e32 v48, 32, v48
	v_ashrrev_i32_e32 v27, 31, v49
	v_or_b32_e32 v27, v118, v27
	v_xor_b32_e32 v49, v49, v27
	v_and_or_b32 v49, v49, s54, v166
	v_or_b32_e32 v49, 32, v49
	v_ashrrev_i32_e32 v26, 31, v50
	v_or_b32_e32 v26, v118, v26
	v_xor_b32_e32 v50, v50, v26
	v_and_or_b32 v50, v50, s54, v79
	v_or_b32_e32 v50, 32, v50
	v_ashrrev_i32_e32 v27, 31, v51
	v_or_b32_e32 v27, v118, v27
	v_xor_b32_e32 v51, v51, v27
	v_and_or_b32 v51, v51, s54, v89
	v_or_b32_e32 v51, 32, v51
	ds_write_b128 v100, v[48:51] offset:832
	v_ashrrev_i32_e32 v26, 31, v52
	v_or_b32_e32 v26, v118, v26
	v_xor_b32_e32 v52, v52, v26
	v_and_or_b32 v52, v52, s54, v165
	v_or_b32_e32 v52, 16, v52
	v_ashrrev_i32_e32 v27, 31, v53
	v_or_b32_e32 v27, v118, v27
	v_xor_b32_e32 v53, v53, v27
	v_and_or_b32 v53, v53, s54, v166
	v_or_b32_e32 v53, 16, v53
	v_ashrrev_i32_e32 v26, 31, v54
	v_or_b32_e32 v26, v118, v26
	v_xor_b32_e32 v54, v54, v26
	v_and_or_b32 v54, v54, s54, v79
	v_or_b32_e32 v54, 16, v54
	v_ashrrev_i32_e32 v27, 31, v55
	v_or_b32_e32 v27, v118, v27
	v_xor_b32_e32 v55, v55, v27
	v_and_or_b32 v55, v55, s54, v89
	v_or_b32_e32 v55, 16, v55
	ds_write_b128 v100, v[52:55] offset:896
	v_ashrrev_i32_e32 v26, 31, v56
	v_or_b32_e32 v26, v118, v26
	v_xor_b32_e32 v56, v56, v26
	v_and_or_b32 v56, v56, s54, v165
	v_ashrrev_i32_e32 v27, 31, v57
	v_or_b32_e32 v27, v118, v27
	v_xor_b32_e32 v57, v57, v27
	v_and_or_b32 v57, v57, s54, v166
	v_ashrrev_i32_e32 v26, 31, v58
	v_or_b32_e32 v26, v118, v26
	v_xor_b32_e32 v58, v58, v26
	v_and_or_b32 v58, v58, s54, v79
	v_ashrrev_i32_e32 v27, 31, v59
	v_or_b32_e32 v27, v118, v27
	v_xor_b32_e32 v59, v59, v27
	v_and_or_b32 v59, v59, s54, v89
	ds_write_b128 v100, v[56:59] offset:960
